# GEMM tile top: counted vmcnt waits only for this tile's first K-step DMA, previous tile's epilogue stores stay in flight
# speedup vs baseline: 1.0017x; 1.0017x over previous
.LBB0_237:
	s_or_b64 exec, exec, s[0:1]
	s_andn2_b64 vcc, exec, s[6:7]
	s_mov_b64 s[0:1], -1
	s_waitcnt lgkmcnt(0)
	s_barrier
	s_cbranch_vccnz .LBB0_503
	v_readlane_b32 s0, v254, 21
	v_readlane_b32 s1, v254, 22
	v_mov_b32_e32 v2, v193
	s_and_b64 vcc, exec, s[0:1]
	s_cbranch_vccz .LBB0_264
	v_ashrrev_i32_e32 v4, 3, v2
	v_ashrrev_i32_e32 v5, 31, v4
	v_readlane_b32 s0, v254, 24
	v_xor_b32_e32 v0, v4, v2
	v_lshlrev_b64 v[6:7], 11, v[4:5]
	v_readlane_b32 s1, v254, 25
	v_lshlrev_b32_e32 v0, 4, v0
	v_and_b32_e32 v0, 0x70, v0
	v_lshl_add_u64 v[8:9], s[0:1], 0, v[6:7]
	v_readlane_b32 s0, v254, 26
	v_readlane_b32 s1, v254, 27
	v_lshl_add_u32 v122, v2, 4, 0
	v_lshl_add_u64 v[98:99], v[8:9], 0, v[0:1]
	v_lshl_add_u64 v[8:9], s[0:1], 0, v[6:7]
	v_readfirstlane_b32 s0, v122
	s_mov_b32 m0, s0
	s_mov_b64 s[0:1], 0x10000
	v_add_u32_e32 v123, 0x1000, v122
	v_lshl_add_u64 v[10:11], v[98:99], 0, s[0:1]
	v_readfirstlane_b32 s0, v123
	s_barrier
	global_load_lds_dwordx4 v[98:99], off
	s_mov_b32 m0, s0
	s_mov_b64 s[0:1], 0x20000
	v_add_u32_e32 v124, 0x2000, v122
	global_load_lds_dwordx4 v[10:11], off
	v_lshl_add_u64 v[10:11], v[98:99], 0, s[0:1]
	v_readfirstlane_b32 s0, v124
	s_mov_b32 m0, s0
	s_mov_b64 s[0:1], 0x30000
	v_add_u32_e32 v125, 0x3000, v122
	global_load_lds_dwordx4 v[10:11], off
	v_lshl_add_u64 v[10:11], v[98:99], 0, s[0:1]
	v_readfirstlane_b32 s0, v125
	v_add_u32_e32 v126, 0x4000, v122
	s_mov_b32 m0, s0
	v_readfirstlane_b32 s0, v126
	global_load_lds_dwordx4 v[10:11], off
	s_mov_b32 m0, s0
	s_movk_i32 s0, 0x60
	v_cmp_gt_i32_e32 vcc, s0, v4
	v_mov_b32_e32 v3, 0x8000
	v_lshl_add_u64 v[114:115], v[8:9], 0, v[0:1]
	v_cndmask_b32_e32 v8, 0, v3, vcc
	v_add_u32_e32 v127, 0x5000, v122
	v_lshlrev_b32_e32 v100, 1, v8
	v_mov_b32_e32 v101, v1
	v_readfirstlane_b32 s0, v127
	global_load_lds_dwordx4 v[114:115], off
	v_lshl_add_u64 v[10:11], v[114:115], 0, v[100:101]
	s_mov_b32 m0, s0
	v_cmp_gt_i32_e32 vcc, 64, v4
	global_load_lds_dwordx4 v[10:11], off
	s_nop 0
	v_cndmask_b32_e32 v10, 0, v199, vcc
	v_add_u32_e32 v128, 0x6000, v122
	v_cmp_gt_i32_e32 vcc, 32, v4
	v_lshlrev_b32_e32 v102, 1, v10
	v_mov_b32_e32 v103, v1
	v_readfirstlane_b32 s0, v128
	v_cndmask_b32_e32 v4, 0, v201, vcc
	v_add_u32_e32 v129, 0x7000, v122
	v_lshl_add_u64 v[12:13], v[114:115], 0, v[102:103]
	s_mov_b32 m0, s0
	v_lshlrev_b32_e32 v104, 1, v4
	v_mov_b32_e32 v105, v1
	v_readfirstlane_b32 s0, v129
	global_load_lds_dwordx4 v[12:13], off
	v_lshl_add_u64 v[12:13], v[114:115], 0, v[104:105]
	s_mov_b32 m0, s0
	v_readlane_b32 s0, v255, 40
	global_load_lds_dwordx4 v[12:13], off
	v_readlane_b32 s1, v255, 41
	v_ashrrev_i32_e32 v12, 7, v2
	s_mov_b32 s3, s1
	v_readlane_b32 s0, v253, 35
	v_lshrrev_b32_e32 v3, 4, v2
	v_bfe_u32 v5, v2, 4, 2
	v_and_b32_e32 v9, 15, v2
	v_bfe_u32 v11, v2, 6, 1
	v_and_b32_e32 v2, 7, v2
	v_lshlrev_b32_e32 v14, 6, v12
	s_lshl_b32 s2, s0, 6
	v_lshl_or_b32 v14, v5, 2, v14
	v_bitop3_b32 v5, v5, v2, 4 bitop3:0x36
	v_bitop3_b32 v2, v3, v2, 3 bitop3:0x6c
	s_movk_i32 s0, 0x210
	v_readlane_b32 s1, v253, 36
	v_lshl_add_u32 v13, v9, 2, 0
	v_lshlrev_b32_e32 v15, 8, v11
	v_lshlrev_b32_e32 v131, 4, v2
	v_mul_lo_u32 v2, v14, s0
	v_add3_u32 v135, v13, v15, v2
	v_lshl_add_u64 v[2:3], s[40:41], 0, v[6:7]
	s_mov_b32 s1, s3
	v_lshl_add_u64 v[106:107], v[2:3], 0, v[0:1]
	v_lshl_add_u64 v[2:3], s[48:49], 0, v[6:7]
	v_writelane_b32 v255, s0, 40
	v_lshlrev_b32_e32 v130, 4, v5
	v_lshlrev_b32_e32 v132, 13, v12
	v_lshlrev_b32_e32 v133, 7, v9
	v_lshlrev_b32_e32 v134, 13, v11
	v_lshl_add_u64 v[108:109], v[2:3], 0, v[0:1]
	v_lshlrev_b32_e32 v0, 1, v8
	v_lshlrev_b32_e32 v110, 1, v10
	v_lshlrev_b32_e32 v112, 1, v4
	v_writelane_b32 v255, s1, 41
	s_lshl_b64 s[0:1], s[2:3], 2
	v_readlane_b32 s2, v254, 36
	s_mov_b32 s66, 1
	s_branch .LBB0_241

.LBB0_241:
	s_mov_b64 s[8:9], 0x80
	v_lshl_add_u64 v[114:115], v[114:115], 0, s[8:9]
	v_mov_b32_e32 v38, 0
	s_mov_b32 s3, s2
	v_lshl_add_u64 v[116:117], v[114:115], 0, v[100:101]
	v_lshl_add_u64 v[118:119], v[114:115], 0, v[102:103]
	v_lshl_add_u64 v[120:121], v[114:115], 0, v[104:105]
	s_mov_b64 s[4:5], 0
	s_mov_b32 s2, 0
	v_readfirstlane_b32 s60, v98
	v_readfirstlane_b32 s61, v99
	v_readfirstlane_b32 s62, v114
	v_readfirstlane_b32 s63, v115
	v_readfirstlane_b32 s64, v122
	v_subrev_u32_e32 v140, s60, v98
	v_subrev_u32_e32 v144, s62, v114
	v_subrev_u32_e32 v145, s62, v116
	v_subrev_u32_e32 v146, s62, v118
	v_subrev_u32_e32 v147, s62, v120
	v_add_u32_e32 v141, 0x10000, v140
	v_add_u32_e32 v142, 0x20000, v140
	v_add_u32_e32 v143, 0x30000, v140
	v_add3_u32 v136, v131, v132, v133
	v_add3_u32 v137, v131, v134, v133
	v_add3_u32 v138, v130, v132, v133
	v_add3_u32 v139, v130, v134, v133
	s_add_u32 s60, s60, 0x80
	s_addc_u32 s61, s61, 0
	s_add_u32 m0, s64, 0x8000
	v_mov_b32_e32 v39, v38
	global_load_lds_dwordx4 v140, s[60:61]
	v_mov_b32_e32 v40, v38
	v_mov_b32_e32 v41, v38
	v_mov_b32_e32 v2, v38
	s_add_u32 m0, s64, 0x9000
	v_mov_b32_e32 v3, v38
	global_load_lds_dwordx4 v141, s[60:61]
	v_mov_b32_e32 v4, v38
	v_mov_b32_e32 v5, v38
	v_mov_b32_e32 v6, v38
	s_add_u32 m0, s64, 0xa000
	v_mov_b32_e32 v7, v38
	global_load_lds_dwordx4 v142, s[60:61]
	v_mov_b32_e32 v8, v38
	v_mov_b32_e32 v9, v38
	v_mov_b32_e32 v10, v38
	s_add_u32 m0, s64, 0xb000
	v_mov_b32_e32 v11, v38
	global_load_lds_dwordx4 v143, s[60:61]
	v_mov_b32_e32 v12, v38
	v_mov_b32_e32 v13, v38
	v_mov_b32_e32 v14, v38
	v_mov_b32_e32 v15, v38
	v_mov_b32_e32 v16, v38
	v_mov_b32_e32 v17, v38
	v_mov_b32_e32 v18, v38
	v_mov_b32_e32 v19, v38
	v_mov_b32_e32 v20, v38
	v_mov_b32_e32 v21, v38
	v_mov_b32_e32 v22, v38
	v_mov_b32_e32 v23, v38
	v_mov_b32_e32 v24, v38
	v_mov_b32_e32 v25, v38
	v_mov_b32_e32 v26, v38
	v_mov_b32_e32 v27, v38
	v_mov_b32_e32 v28, v38
	v_mov_b32_e32 v29, v38
	v_mov_b32_e32 v30, v38
	v_mov_b32_e32 v31, v38
	v_mov_b32_e32 v32, v38
	v_mov_b32_e32 v33, v38
	v_mov_b32_e32 v34, v38
	v_mov_b32_e32 v35, v38
	v_mov_b32_e32 v36, v38
	v_mov_b32_e32 v37, v38
	v_mov_b32_e32 v42, v38
	v_mov_b32_e32 v43, v38
	v_mov_b32_e32 v44, v38
	v_mov_b32_e32 v45, v38
	v_mov_b32_e32 v46, v38
	v_mov_b32_e32 v47, v38
	v_mov_b32_e32 v48, v38
	v_mov_b32_e32 v49, v38
	v_mov_b32_e32 v50, v38
	v_mov_b32_e32 v51, v38
	v_mov_b32_e32 v52, v38
	v_mov_b32_e32 v53, v38
	v_mov_b32_e32 v54, v38
	v_mov_b32_e32 v55, v38
	v_mov_b32_e32 v56, v38
	v_mov_b32_e32 v57, v38
	v_mov_b32_e32 v58, v38
	v_mov_b32_e32 v59, v38
	v_mov_b32_e32 v60, v38
	v_mov_b32_e32 v61, v38
	v_mov_b32_e32 v62, v38
	v_mov_b32_e32 v63, v38
	v_mov_b32_e32 v64, v38
	v_mov_b32_e32 v65, v38
	s_add_u32 s60, s60, 0x80
	s_addc_u32 s61, s61, 0
	s_mov_b64 s[10:11], 0x10080
	s_mov_b64 s[12:13], 0x20080
	s_mov_b64 s[14:15], 0x30080
	s_cmp_eq_u32 s66, 0
	s_mov_b32 s66, 0
	s_cbranch_scc1 .Lodwin_wlate
	s_waitcnt vmcnt(4) lgkmcnt(0)
	s_branch .Lodwin_go
.Lodwin_wlate:
	s_waitcnt vmcnt(12) lgkmcnt(0)
.Lodwin_go:
	s_barrier
	ds_read_b128 v[66:69], v136 offset:0
	ds_read_b128 v[82:85], v137 offset:16384
	ds_read_b128 v[86:89], v137 offset:18432
	ds_read_b128 v[70:73], v136 offset:2048
	ds_read_b128 v[90:93], v137 offset:20480
	ds_read_b128 v[94:97], v137 offset:22528
	ds_read_b128 v[74:77], v136 offset:4096
	ds_read_b128 v[78:81], v136 offset:6144
	s_mov_b32 s65, 7

.LBB0_503:
	s_and_b64 vcc, exec, s[0:1]
	s_cbranch_vccz .LBB0_878
	v_readlane_b32 s0, v254, 28
	v_readlane_b32 s1, v254, 29
	v_mov_b32_e32 v2, v193
	s_andn2_b64 vcc, exec, s[0:1]
	s_cbranch_vccnz .LBB0_548
	v_ashrrev_i32_e32 v4, 3, v2
	v_ashrrev_i32_e32 v5, 31, v4
	v_readlane_b32 s0, v254, 30
	v_xor_b32_e32 v0, v4, v2
	v_lshlrev_b64 v[6:7], 11, v[4:5]
	v_readlane_b32 s1, v254, 31
	v_lshlrev_b32_e32 v0, 4, v0
	v_and_b32_e32 v0, 0x70, v0
	v_lshl_add_u64 v[8:9], s[0:1], 0, v[6:7]
	v_readlane_b32 s0, v254, 32
	v_readlane_b32 s1, v254, 33
	v_lshl_add_u32 v112, v2, 4, 0
	v_lshl_add_u64 v[98:99], v[8:9], 0, v[0:1]
	v_lshl_add_u64 v[8:9], s[0:1], 0, v[6:7]
	v_readfirstlane_b32 s0, v112
	s_mov_b32 m0, s0
	s_mov_b64 s[0:1], 0x10000
	v_add_u32_e32 v113, 0x1000, v112
	v_lshl_add_u64 v[10:11], v[98:99], 0, s[0:1]
	v_readfirstlane_b32 s0, v113
	s_barrier
	global_load_lds_dwordx4 v[98:99], off
	s_mov_b32 m0, s0
	s_mov_b64 s[0:1], 0x20000
	v_add_u32_e32 v114, 0x2000, v112
	global_load_lds_dwordx4 v[10:11], off
	v_lshl_add_u64 v[10:11], v[98:99], 0, s[0:1]
	v_readfirstlane_b32 s0, v114
	s_mov_b32 m0, s0
	s_mov_b64 s[0:1], 0x30000
	v_add_u32_e32 v115, 0x3000, v112
	global_load_lds_dwordx4 v[10:11], off
	v_lshl_add_u64 v[10:11], v[98:99], 0, s[0:1]
	v_readfirstlane_b32 s0, v115
	v_add_u32_e32 v116, 0x4000, v112
	v_add_u32_e32 v117, 32, v4
	v_readlane_b32 s2, v254, 35
	s_mov_b32 m0, s0
	v_readfirstlane_b32 s0, v116
	v_cmp_gt_i32_e32 vcc, s2, v117
	v_add_u32_e32 v118, 0x5000, v112
	global_load_lds_dwordx4 v[10:11], off
	v_lshl_add_u64 v[66:67], v[8:9], 0, v[0:1]
	s_mov_b32 m0, s0
	v_cndmask_b32_e32 v8, 0, v199, vcc
	v_mov_b32_e32 v9, v1
	v_readfirstlane_b32 s0, v118
	v_add_u32_e32 v119, 64, v4
	global_load_lds_dwordx4 v[66:67], off
	v_lshl_add_u64 v[8:9], v[66:67], 0, v[8:9]
	s_mov_b32 m0, s0
	v_cmp_gt_i32_e32 vcc, s2, v119
	v_add_u32_e32 v120, 0x6000, v112
	v_add_u32_e32 v121, 0x60, v4
	global_load_lds_dwordx4 v[8:9], off
	v_cndmask_b32_e32 v8, 0, v206, vcc
	v_mov_b32_e32 v9, v1
	v_readfirstlane_b32 s0, v120
	v_cmp_gt_i32_e32 vcc, s2, v121
	v_add_u32_e32 v122, 0x7000, v112
	v_lshl_add_u64 v[8:9], v[66:67], 0, v[8:9]
	s_mov_b32 m0, s0
	v_cndmask_b32_e32 v4, 0, v207, vcc
	v_mov_b32_e32 v5, v1
	v_readfirstlane_b32 s0, v122
	global_load_lds_dwordx4 v[8:9], off
	v_lshl_add_u64 v[4:5], v[66:67], 0, v[4:5]
	s_mov_b32 m0, s0
	v_ashrrev_i32_e32 v9, 7, v2
	global_load_lds_dwordx4 v[4:5], off
	v_lshrrev_b32_e32 v3, 4, v2
	v_bfe_u32 v4, v2, 4, 2
	v_and_b32_e32 v5, 15, v2
	v_bfe_u32 v8, v2, 6, 1
	v_and_b32_e32 v2, 7, v2
	v_lshlrev_b32_e32 v11, 6, v9
	v_lshl_or_b32 v11, v4, 2, v11
	v_bitop3_b32 v4, v4, v2, 4 bitop3:0x36
	v_bitop3_b32 v2, v3, v2, 3 bitop3:0x6c
	s_movk_i32 s0, 0x210
	v_lshl_add_u32 v10, v5, 2, 0
	v_lshlrev_b32_e32 v12, 8, v8
	v_lshlrev_b32_e32 v124, 4, v2
	v_mul_lo_u32 v2, v11, s0
	v_add3_u32 v128, v10, v12, v2
	v_lshl_add_u64 v[2:3], s[40:41], 0, v[6:7]
	v_lshl_add_u64 v[100:101], v[2:3], 0, v[0:1]
	v_lshl_add_u64 v[2:3], s[48:49], 0, v[6:7]
	v_lshlrev_b32_e32 v123, 4, v4
	v_lshlrev_b32_e32 v125, 13, v9
	v_lshlrev_b32_e32 v126, 7, v5
	v_lshlrev_b32_e32 v127, 13, v8
	v_lshl_add_u64 v[102:103], v[2:3], 0, v[0:1]
	v_readlane_b32 s3, v254, 36
	s_mov_b32 s66, 1
	s_branch .LBB0_508

.LBB0_508:
	v_cmp_gt_i32_e32 vcc, s2, v117
	s_mov_b64 s[0:1], 0x80
	v_lshl_add_u64 v[104:105], v[66:67], 0, s[0:1]
	v_cndmask_b32_e32 v0, 0, v199, vcc
	v_cmp_gt_i32_e32 vcc, s2, v119
	v_mov_b32_e32 v3, v1
	v_mov_b32_e32 v5, v1
	v_cndmask_b32_e32 v2, 0, v206, vcc
	v_cmp_gt_i32_e32 vcc, s2, v121
	v_mov_b32_e32 v42, 0
	s_mov_b32 s4, 0
	v_cndmask_b32_e32 v4, 0, v207, vcc
	v_lshl_add_u64 v[106:107], v[104:105], 0, v[0:1]
	v_lshl_add_u64 v[108:109], v[104:105], 0, v[2:3]
	v_lshl_add_u64 v[110:111], v[104:105], 0, v[4:5]
	s_mov_b64 s[0:1], 0
	v_readfirstlane_b32 s60, v98
	v_readfirstlane_b32 s61, v99
	v_readfirstlane_b32 s62, v104
	v_readfirstlane_b32 s63, v105
	v_readfirstlane_b32 s64, v112
	v_subrev_u32_e32 v140, s60, v98
	v_subrev_u32_e32 v144, s62, v104
	v_subrev_u32_e32 v145, s62, v106
	v_subrev_u32_e32 v146, s62, v108
	v_subrev_u32_e32 v147, s62, v110
	v_add_u32_e32 v141, 0x10000, v140
	v_add_u32_e32 v142, 0x20000, v140
	v_add_u32_e32 v143, 0x30000, v140
	v_add3_u32 v136, v124, v125, v126
	v_add3_u32 v137, v124, v127, v126
	v_add3_u32 v138, v123, v125, v126
	v_add3_u32 v139, v123, v127, v126
	s_add_u32 s60, s60, 0x80
	s_addc_u32 s61, s61, 0
	s_add_u32 m0, s64, 0x8000
	v_mov_b32_e32 v43, v42
	global_load_lds_dwordx4 v140, s[60:61]
	v_mov_b32_e32 v44, v42
	v_mov_b32_e32 v45, v42
	v_mov_b32_e32 v2, v42
	s_add_u32 m0, s64, 0x9000
	v_mov_b32_e32 v3, v42
	global_load_lds_dwordx4 v141, s[60:61]
	v_mov_b32_e32 v4, v42
	v_mov_b32_e32 v5, v42
	v_mov_b32_e32 v6, v42
	s_add_u32 m0, s64, 0xa000
	v_mov_b32_e32 v7, v42
	global_load_lds_dwordx4 v142, s[60:61]
	v_mov_b32_e32 v8, v42
	v_mov_b32_e32 v9, v42
	v_mov_b32_e32 v10, v42
	s_add_u32 m0, s64, 0xb000
	v_mov_b32_e32 v11, v42
	global_load_lds_dwordx4 v143, s[60:61]
	v_mov_b32_e32 v12, v42
	v_mov_b32_e32 v13, v42
	v_mov_b32_e32 v14, v42
	v_mov_b32_e32 v15, v42
	v_mov_b32_e32 v16, v42
	v_mov_b32_e32 v17, v42
	v_mov_b32_e32 v18, v42
	v_mov_b32_e32 v19, v42
	v_mov_b32_e32 v20, v42
	v_mov_b32_e32 v21, v42
	v_mov_b32_e32 v22, v42
	v_mov_b32_e32 v23, v42
	v_mov_b32_e32 v24, v42
	v_mov_b32_e32 v25, v42
	v_mov_b32_e32 v26, v42
	v_mov_b32_e32 v27, v42
	v_mov_b32_e32 v28, v42
	v_mov_b32_e32 v29, v42
	v_mov_b32_e32 v30, v42
	v_mov_b32_e32 v31, v42
	v_mov_b32_e32 v32, v42
	v_mov_b32_e32 v33, v42
	v_mov_b32_e32 v34, v42
	v_mov_b32_e32 v35, v42
	v_mov_b32_e32 v36, v42
	v_mov_b32_e32 v37, v42
	v_mov_b32_e32 v38, v42
	v_mov_b32_e32 v39, v42
	v_mov_b32_e32 v40, v42
	v_mov_b32_e32 v41, v42
	v_mov_b32_e32 v46, v42
	v_mov_b32_e32 v47, v42
	v_mov_b32_e32 v48, v42
	v_mov_b32_e32 v49, v42
	v_mov_b32_e32 v50, v42
	v_mov_b32_e32 v51, v42
	v_mov_b32_e32 v52, v42
	v_mov_b32_e32 v53, v42
	v_mov_b32_e32 v54, v42
	v_mov_b32_e32 v55, v42
	v_mov_b32_e32 v56, v42
	v_mov_b32_e32 v57, v42
	v_mov_b32_e32 v58, v42
	v_mov_b32_e32 v59, v42
	v_mov_b32_e32 v60, v42
	v_mov_b32_e32 v61, v42
	v_mov_b32_e32 v62, v42
	v_mov_b32_e32 v63, v42
	v_mov_b32_e32 v64, v42
	v_mov_b32_e32 v65, v42
	s_add_u32 s60, s60, 0x80
	s_addc_u32 s61, s61, 0
	s_mov_b64 s[12:13], 0x10000
	s_mov_b64 s[14:15], 0x20000
	s_mov_b64 s[16:17], 0x30000
	s_mov_b64 s[8:9], 0x10080
	s_mov_b64 s[10:11], 0x20080
	s_mov_b64 s[18:19], 0x30080
	s_cmp_eq_u32 s66, 0
	s_mov_b32 s66, 0
	s_cbranch_scc1 .Levwin_wlate
	s_waitcnt vmcnt(4) lgkmcnt(0)
	s_branch .Levwin_go

.LBB0_878:
	v_readlane_b32 s2, v253, 32
	s_cmp_lg_u32 s2, 3
	s_cselect_b64 s[0:1], -1, 0
	s_cmp_eq_u32 s2, 3
	s_cselect_b64 s[4:5], -1, 0
	s_and_b64 s[2:3], s[4:5], exec
	s_movk_i32 s2, 0x480
	s_cselect_b32 s2, 0x400, s2
	v_readlane_b32 s3, v254, 36
	v_mov_b32_e32 v2, v193
	s_cmp_ge_i32 s3, s2
	s_cbranch_scc1 .LBB0_888
	s_and_b64 s[4:5], s[4:5], exec
	s_cselect_b32 s9, 8, 6
	s_cselect_b32 s8, 16, 18
	s_lshl_b32 s10, s9, 3
	v_cvt_f32_ubyte0_e32 v0, s10
	v_rcp_iflag_f32_e32 v0, v0
	s_sub_i32 s3, 0, s10
	v_readlane_b32 s12, v254, 39
	s_abs_i32 s5, s12
	v_mul_f32_e32 v0, 0x4f7ffffe, v0
	v_cvt_u32_f32_e32 v0, v0
	s_ashr_i32 s4, s12, 31
	v_readlane_b32 s16, v253, 33
	v_readlane_b32 s17, v253, 34
	v_readfirstlane_b32 s6, v0
	s_mul_i32 s3, s3, s6
	s_mul_hi_u32 s3, s6, s3
	s_add_i32 s3, s6, s3
	s_mul_hi_u32 s6, s5, s3
	s_mul_i32 s7, s6, s10
	s_sub_i32 s5, s5, s7
	s_add_i32 s11, s6, 1
	s_sub_i32 s7, s5, s10
	s_cmp_ge_u32 s5, s10
	s_cselect_b32 s6, s11, s6
	s_cselect_b32 s5, s7, s5
	s_add_i32 s7, s6, 1
	s_cmp_ge_u32 s5, s10
	s_cselect_b32 s5, s7, s6
	s_xor_b32 s5, s5, s4
	s_sub_i32 s4, s5, s4
	s_mul_i32 s4, s4, s9
	s_sub_i32 s5, s8, s4
	s_min_u32 s5, s9, s5
	v_cvt_f32_ubyte0_e32 v0, s5
	v_rcp_iflag_f32_e32 v0, v0
	s_lshl_b32 s6, s4, 3
	s_sub_i32 s6, s12, s6
	s_sub_i32 s12, 0, s5
	v_mul_f32_e32 v0, 0x4f7ffffe, v0
	v_cvt_u32_f32_e32 v0, v0
	s_abs_i32 s11, s6
	s_ashr_i32 s7, s6, 31
	v_ashrrev_i32_e32 v4, 3, v2
	v_readfirstlane_b32 s13, v0
	s_mul_i32 s12, s12, s13
	s_mul_hi_u32 s12, s13, s12
	s_add_i32 s13, s13, s12
	s_mul_hi_u32 s12, s11, s13
	s_mul_i32 s13, s12, s5
	s_sub_i32 s11, s11, s13
	s_add_i32 s13, s12, 1
	s_sub_i32 s14, s11, s5
	s_cmp_ge_u32 s11, s5
	s_cselect_b32 s12, s13, s12
	s_cselect_b32 s11, s14, s11
	s_add_i32 s13, s12, 1
	s_cmp_ge_u32 s11, s5
	s_cselect_b32 s11, s13, s12
	s_xor_b32 s11, s11, s7
	s_sub_i32 s12, s11, s7
	v_readlane_b32 s7, v254, 23
	s_mul_i32 s7, s7, s8
	s_mul_i32 s5, s12, s5
	s_add_i32 s4, s4, s7
	s_sub_i32 s5, s6, s5
	s_add_i32 s6, s4, s5
	s_and_b64 s[4:5], s[16:17], exec
	s_mov_b32 s4, 0x5b3c000
	s_cselect_b32 s4, s4, 0x133c000
	s_add_u32 s4, s48, s4
	s_addc_u32 s5, s49, 0
	s_ashr_i32 s7, s6, 31
	s_lshl_b64 s[6:7], s[6:7], 18
	s_add_u32 s14, s4, s6
	s_addc_u32 s15, s5, s7
	s_and_b64 s[6:7], s[16:17], exec
	s_mov_b32 s6, 0x7c0000
	s_cselect_b32 s6, s6, 0x800000
	s_add_u32 s6, s48, s6
	s_addc_u32 s7, s49, 0
	s_ashr_i32 s13, s12, 31
	v_xor_b32_e32 v3, v4, v2
	s_lshl_b64 s[12:13], s[12:13], 18
	v_ashrrev_i32_e32 v5, 31, v4
	s_add_u32 s12, s6, s12
	v_lshlrev_b64 v[6:7], 11, v[4:5]
	v_lshlrev_b32_e32 v0, 4, v3
	v_lshl_add_u32 v122, v2, 4, 0
	s_addc_u32 s13, s7, s13
	v_lshl_add_u64 v[8:9], s[14:15], 0, v[6:7]
	v_and_b32_e32 v0, 0x70, v0
	v_readfirstlane_b32 s11, v122
	v_add_u32_e32 v123, 0x1000, v122
	v_lshl_add_u64 v[104:105], v[8:9], 0, v[0:1]
	v_lshl_add_u64 v[8:9], s[12:13], 0, v[6:7]
	s_mov_b32 m0, s11
	s_mov_b64 s[12:13], 0x10000
	v_readfirstlane_b32 s11, v123
	v_add_u32_e32 v124, 0x2000, v122
	s_barrier
	global_load_lds_dwordx4 v[104:105], off
	v_lshl_add_u64 v[10:11], v[104:105], 0, s[12:13]
	s_mov_b32 m0, s11
	s_mov_b64 s[12:13], 0x20000
	v_readfirstlane_b32 s11, v124
	v_add_u32_e32 v125, 0x3000, v122
	global_load_lds_dwordx4 v[10:11], off
	v_lshl_add_u64 v[10:11], v[104:105], 0, s[12:13]
	s_mov_b32 m0, s11
	s_mov_b64 s[12:13], 0x30000
	v_readfirstlane_b32 s11, v125
	v_add_u32_e32 v126, 0x4000, v122
	global_load_lds_dwordx4 v[10:11], off
	v_lshl_add_u64 v[10:11], v[104:105], 0, s[12:13]
	s_mov_b32 m0, s11
	v_readfirstlane_b32 s11, v126
	global_load_lds_dwordx4 v[10:11], off
	s_mov_b32 m0, s11
	s_movk_i32 s11, 0x60
	v_cmp_gt_i32_e32 vcc, s11, v4
	v_mov_b32_e32 v3, 0x8000
	v_lshl_add_u64 v[70:71], v[8:9], 0, v[0:1]
	v_cndmask_b32_e32 v8, 0, v3, vcc
	v_add_u32_e32 v127, 0x5000, v122
	v_lshlrev_b32_e32 v98, 1, v8
	v_mov_b32_e32 v99, v1
	v_readfirstlane_b32 s11, v127
	global_load_lds_dwordx4 v[70:71], off
	v_lshl_add_u64 v[10:11], v[70:71], 0, v[98:99]
	s_mov_b32 m0, s11
	v_cmp_gt_i32_e32 vcc, 64, v4
	global_load_lds_dwordx4 v[10:11], off
	s_nop 0
	v_cndmask_b32_e32 v10, 0, v199, vcc
	v_add_u32_e32 v128, 0x6000, v122
	v_cmp_gt_i32_e32 vcc, 32, v4
	v_lshlrev_b32_e32 v100, 1, v10
	v_mov_b32_e32 v101, v1
	v_readfirstlane_b32 s11, v128
	v_cndmask_b32_e32 v4, 0, v201, vcc
	v_add_u32_e32 v129, 0x7000, v122
	v_lshl_add_u64 v[12:13], v[70:71], 0, v[100:101]
	s_mov_b32 m0, s11
	v_lshlrev_b32_e32 v102, 1, v4
	v_mov_b32_e32 v103, v1
	v_readfirstlane_b32 s11, v129
	global_load_lds_dwordx4 v[12:13], off
	v_lshl_add_u64 v[12:13], v[70:71], 0, v[102:103]
	s_mov_b32 m0, s11
	v_lshrrev_b32_e32 v3, 4, v2
	global_load_lds_dwordx4 v[12:13], off
	v_ashrrev_i32_e32 v12, 7, v2
	v_bfe_u32 v5, v2, 4, 2
	v_and_b32_e32 v9, 15, v2
	v_bfe_u32 v11, v2, 6, 1
	v_and_b32_e32 v2, 7, v2
	v_lshlrev_b32_e32 v14, 6, v12
	v_lshl_or_b32 v14, v5, 2, v14
	v_bitop3_b32 v5, v5, v2, 4 bitop3:0x36
	v_bitop3_b32 v2, v3, v2, 3 bitop3:0x6c
	s_movk_i32 s11, 0x210
	v_lshl_add_u32 v13, v9, 2, 0
	v_lshlrev_b32_e32 v15, 8, v11
	v_lshlrev_b32_e32 v131, 4, v2
	v_mul_lo_u32 v2, v14, s11
	v_add3_u32 v135, v13, v15, v2
	v_lshl_add_u64 v[2:3], s[4:5], 0, v[6:7]
	v_lshl_add_u64 v[106:107], v[2:3], 0, v[0:1]
	v_lshl_add_u64 v[2:3], s[6:7], 0, v[6:7]
	v_lshlrev_b32_e32 v130, 4, v5
	v_lshlrev_b32_e32 v132, 13, v12
	v_lshlrev_b32_e32 v133, 7, v9
	v_lshlrev_b32_e32 v134, 13, v11
	v_lshl_add_u64 v[108:109], v[2:3], 0, v[0:1]
	v_lshlrev_b32_e32 v0, 1, v8
	v_lshlrev_b32_e32 v110, 1, v10
	v_lshlrev_b32_e32 v112, 1, v4
	v_readlane_b32 s6, v254, 36
	s_mov_b32 s72, 1
	s_branch .LBB0_882

.LBB0_882:
	s_mov_b64 s[14:15], 0x80
	v_lshl_add_u64 v[114:115], v[70:71], 0, s[14:15]
	v_mov_b32_e32 v38, 0
	s_mov_b32 s7, s6
	v_lshl_add_u64 v[116:117], v[114:115], 0, v[98:99]
	v_lshl_add_u64 v[118:119], v[114:115], 0, v[100:101]
	v_lshl_add_u64 v[120:121], v[114:115], 0, v[102:103]
	s_mov_b64 s[4:5], 0
	s_mov_b32 s6, 0
	v_readfirstlane_b32 s60, v104
	v_readfirstlane_b32 s61, v105
	v_readfirstlane_b32 s62, v114
	v_readfirstlane_b32 s63, v115
	v_readfirstlane_b32 s64, v122
	v_subrev_u32_e32 v140, s60, v104
	v_subrev_u32_e32 v144, s62, v114
	v_subrev_u32_e32 v145, s62, v116
	v_subrev_u32_e32 v146, s62, v118
	v_subrev_u32_e32 v147, s62, v120
	v_add_u32_e32 v141, 0x10000, v140
	v_add_u32_e32 v142, 0x20000, v140
	v_add_u32_e32 v143, 0x30000, v140
	v_add3_u32 v136, v131, v132, v133
	v_add3_u32 v137, v131, v134, v133
	v_add3_u32 v138, v130, v132, v133
	v_add3_u32 v139, v130, v134, v133
	s_add_u32 s60, s60, 0x80
	s_addc_u32 s61, s61, 0
	s_add_u32 m0, s64, 0x8000
	v_mov_b32_e32 v39, v38
	global_load_lds_dwordx4 v140, s[60:61]
	v_mov_b32_e32 v40, v38
	v_mov_b32_e32 v41, v38
	v_mov_b32_e32 v2, v38
	s_add_u32 m0, s64, 0x9000
	v_mov_b32_e32 v3, v38
	global_load_lds_dwordx4 v141, s[60:61]
	v_mov_b32_e32 v4, v38
	v_mov_b32_e32 v5, v38
	v_mov_b32_e32 v6, v38
	s_add_u32 m0, s64, 0xa000
	v_mov_b32_e32 v7, v38
	global_load_lds_dwordx4 v142, s[60:61]
	v_mov_b32_e32 v8, v38
	v_mov_b32_e32 v9, v38
	v_mov_b32_e32 v10, v38
	s_add_u32 m0, s64, 0xb000
	v_mov_b32_e32 v11, v38
	global_load_lds_dwordx4 v143, s[60:61]
	v_mov_b32_e32 v12, v38
	v_mov_b32_e32 v13, v38
	v_mov_b32_e32 v14, v38
	v_mov_b32_e32 v15, v38
	v_mov_b32_e32 v16, v38
	v_mov_b32_e32 v17, v38
	v_mov_b32_e32 v18, v38
	v_mov_b32_e32 v19, v38
	v_mov_b32_e32 v20, v38
	v_mov_b32_e32 v21, v38
	v_mov_b32_e32 v22, v38
	v_mov_b32_e32 v23, v38
	v_mov_b32_e32 v24, v38
	v_mov_b32_e32 v25, v38
	v_mov_b32_e32 v26, v38
	v_mov_b32_e32 v27, v38
	v_mov_b32_e32 v28, v38
	v_mov_b32_e32 v29, v38
	v_mov_b32_e32 v30, v38
	v_mov_b32_e32 v31, v38
	v_mov_b32_e32 v32, v38
	v_mov_b32_e32 v33, v38
	v_mov_b32_e32 v34, v38
	v_mov_b32_e32 v35, v38
	v_mov_b32_e32 v36, v38
	v_mov_b32_e32 v37, v38
	v_mov_b32_e32 v42, v38
	v_mov_b32_e32 v43, v38
	v_mov_b32_e32 v44, v38
	v_mov_b32_e32 v45, v38
	v_mov_b32_e32 v46, v38
	v_mov_b32_e32 v47, v38
	v_mov_b32_e32 v48, v38
	v_mov_b32_e32 v49, v38
	v_mov_b32_e32 v50, v38
	v_mov_b32_e32 v51, v38
	v_mov_b32_e32 v52, v38
	v_mov_b32_e32 v53, v38
	v_mov_b32_e32 v54, v38
	v_mov_b32_e32 v55, v38
	v_mov_b32_e32 v56, v38
	v_mov_b32_e32 v57, v38
	v_mov_b32_e32 v58, v38
	v_mov_b32_e32 v59, v38
	v_mov_b32_e32 v60, v38
	v_mov_b32_e32 v61, v38
	v_mov_b32_e32 v62, v38
	v_mov_b32_e32 v63, v38
	v_mov_b32_e32 v64, v38
	v_mov_b32_e32 v65, v38
	s_add_u32 s60, s60, 0x80
	s_addc_u32 s61, s61, 0
	s_mov_b64 s[22:23], 0x10000
	s_mov_b64 s[24:25], 0x20000
	s_mov_b64 s[26:27], 0x30000
	s_mov_b64 s[16:17], 0x10080
	s_mov_b64 s[18:19], 0x20080
	s_mov_b64 s[20:21], 0x30080
	s_cmp_eq_u32 s72, 0
	s_mov_b32 s72, 0
	s_cbranch_scc1 .Lwout_wlate
	s_waitcnt vmcnt(4) lgkmcnt(0)
	s_branch .Lwout_go
.Lwout_wlate:
	s_waitcnt vmcnt(20) lgkmcnt(0)
